# NSA: quad reductions of importance sums via DPP (no ds_bpermute), cross-half row-max exchange via v_permlane32_swap (no LDS round trip)
# speedup vs baseline: 1.0501x; 1.0010x over previous
; DI void nsa_attn_phase(int wv, const P& p_, LAS unsigned char* lds) {
;     ...
;         for (int sub = 0; sub < 2; ++sub) {
; #pragma unroll
;           for (int reg = 0; reg < 16; ++reg) { const float v = s[sub][reg]; s[sub][reg] = v > -1e29f ? __builtin_amdgcn_exp2f(v - m) * inv : 0.f; }
; #pragma unroll
;           for (int lg = 0; lg < 4; ++lg) { float G = s[sub][4 * lg] + s[sub][4 * lg + 1] + s[sub][4 * lg + 2] + s[sub][4 * lg + 3], Lv = s[sub][4 * lg + 3];
;             G += __shfl_xor(G, 1); G += __shfl_xor(G, 2); Lv += __shfl_xor(Lv, 1); Lv += __shfl_xor(Lv, 2);
;             if (hd == 0) { gp[8 * sub + 2 * lg] = G; gp[4096 + 8 * sub + 2 * lg] = Lv; } }
.LBB0_698:
	s_nop 0
	v_sub_f32_e32 v66, v0, v154
	v_exp_f32_e32 v66, v66
	v_sub_f32_e32 v67, v1, v154
	v_exp_f32_e32 v67, v67
	v_cmp_lt_f32_e32 vcc, s56, v0
	v_mul_f32_e32 v66, v155, v66
	v_add_u32_e32 v70, 0, v166
	v_cndmask_b32_e32 v66, 0, v66, vcc
	v_mul_f32_e32 v0, v155, v67
	v_sub_f32_e32 v67, v2, v154
	v_cmp_lt_f32_e32 vcc, s56, v1
	v_exp_f32_e32 v68, v67
	s_nop 0
	v_cndmask_b32_e32 v67, 0, v0, vcc
	v_sub_f32_e32 v0, v3, v154
	v_exp_f32_e32 v0, v0
	v_mul_f32_e32 v1, v155, v68
	v_cmp_lt_f32_e32 vcc, s56, v2
	v_mul_f32_e32 v0, v155, v0
	s_nop 0
	v_cndmask_b32_e32 v68, 0, v1, vcc
	v_cmp_lt_f32_e32 vcc, s56, v3
	s_nop 1
	v_cndmask_b32_e32 v69, 0, v0, vcc
	v_add_f32_e32 v0, v66, v67
	v_add_f32_e32 v0, v68, v0
	v_add_f32_e32 v0, v69, v0
	v_mov_b32_e32 v2, v69
	s_nop 0
	v_add_f32_dpp v0, v0, v0 quad_perm:[1,0,3,2] row_mask:0xf bank_mask:0xf
	v_add_f32_dpp v2, v2, v2 quad_perm:[1,0,3,2] row_mask:0xf bank_mask:0xf
	s_nop 0
	v_add_f32_dpp v0, v0, v0 quad_perm:[2,3,0,1] row_mask:0xf bank_mask:0xf
	v_add_f32_dpp v2, v2, v2 quad_perm:[2,3,0,1] row_mask:0xf bank_mask:0xf
	s_and_saveexec_b64 s[0:1], s[6:7]
	s_cbranch_execz .LBB0_700
	ds_write2st64_b32 v70, v0, v2 offset1:64
.LBB0_700:
	s_or_b64 exec, exec, s[0:1]
	v_sub_f32_e32 v0, v4, v154
	v_exp_f32_e32 v0, v0
	s_waitcnt lgkmcnt(1)
	v_sub_f32_e32 v1, v5, v154
	v_exp_f32_e32 v1, v1
	v_cmp_lt_f32_e32 vcc, s56, v4
	v_mul_f32_e32 v0, v155, v0
	s_nop 0
	v_cndmask_b32_e32 v71, 0, v0, vcc
	v_mul_f32_e32 v0, v155, v1
	v_sub_f32_e32 v1, v6, v154
	v_cmp_lt_f32_e32 vcc, s56, v5
	v_exp_f32_e32 v1, v1
	s_nop 0
	v_cndmask_b32_e32 v72, 0, v0, vcc
	v_sub_f32_e32 v0, v7, v154
	v_exp_f32_e32 v0, v0
	v_mul_f32_e32 v1, v155, v1
	v_cmp_lt_f32_e32 vcc, s56, v6
	v_mul_f32_e32 v0, v155, v0
	s_nop 0
	v_cndmask_b32_e32 v73, 0, v1, vcc
	v_cmp_lt_f32_e32 vcc, s56, v7
	s_nop 1
	v_cndmask_b32_e32 v74, 0, v0, vcc
	v_add_f32_e32 v0, v71, v72
	v_add_f32_e32 v0, v73, v0
	v_add_f32_e32 v0, v74, v0
	v_mov_b32_e32 v2, v74
	s_nop 0
	v_add_f32_dpp v0, v0, v0 quad_perm:[1,0,3,2] row_mask:0xf bank_mask:0xf
	v_add_f32_dpp v2, v2, v2 quad_perm:[1,0,3,2] row_mask:0xf bank_mask:0xf
	s_nop 0
	v_add_f32_dpp v0, v0, v0 quad_perm:[2,3,0,1] row_mask:0xf bank_mask:0xf
	v_add_f32_dpp v2, v2, v2 quad_perm:[2,3,0,1] row_mask:0xf bank_mask:0xf
	s_and_saveexec_b64 s[0:1], s[6:7]
	s_cbranch_execz .LBB0_702
	v_add_u32_e32 v1, 8, v70
	ds_write2st64_b32 v1, v0, v2 offset1:64
.LBB0_702:
	s_or_b64 exec, exec, s[0:1]
	v_sub_f32_e32 v0, v8, v154
	v_exp_f32_e32 v0, v0
	s_waitcnt lgkmcnt(1)
	v_sub_f32_e32 v1, v9, v154
	v_exp_f32_e32 v1, v1
	v_sub_f32_e32 v2, v10, v154
	v_exp_f32_e32 v2, v2
	s_waitcnt lgkmcnt(0)
	v_sub_f32_e32 v3, v11, v154
	v_exp_f32_e32 v3, v3
	v_mul_f32_e32 v0, v155, v0
	v_cmp_lt_f32_e32 vcc, s56, v8
	v_mul_f32_e32 v1, v155, v1
	v_mul_f32_e32 v2, v155, v2
	v_cndmask_b32_e32 v0, 0, v0, vcc
	v_cmp_lt_f32_e32 vcc, s56, v9
	v_mul_f32_e32 v3, v155, v3
	s_nop 0
	v_cndmask_b32_e32 v1, 0, v1, vcc
	v_cmp_lt_f32_e32 vcc, s56, v10
	v_add_f32_e32 v4, v0, v1
	s_nop 0
	v_cndmask_b32_e32 v2, 0, v2, vcc
	v_cmp_lt_f32_e32 vcc, s56, v11
	v_add_f32_e32 v4, v2, v4
	s_nop 0
	v_cndmask_b32_e32 v3, 0, v3, vcc
	v_add_f32_e32 v4, v3, v4
	v_mov_b32_e32 v6, v3
	s_nop 0
	v_add_f32_dpp v4, v4, v4 quad_perm:[1,0,3,2] row_mask:0xf bank_mask:0xf
	v_add_f32_dpp v6, v6, v6 quad_perm:[1,0,3,2] row_mask:0xf bank_mask:0xf
	s_nop 0
	v_add_f32_dpp v4, v4, v4 quad_perm:[2,3,0,1] row_mask:0xf bank_mask:0xf
	v_add_f32_dpp v6, v6, v6 quad_perm:[2,3,0,1] row_mask:0xf bank_mask:0xf
	s_and_saveexec_b64 s[0:1], s[6:7]
	s_cbranch_execz .LBB0_704
	v_add_u32_e32 v5, 16, v70
	ds_write2st64_b32 v5, v4, v6 offset1:64
.LBB0_704:
	s_or_b64 exec, exec, s[0:1]
	v_sub_f32_e32 v4, v12, v154
	v_exp_f32_e32 v4, v4
	s_waitcnt lgkmcnt(1)
	v_sub_f32_e32 v5, v13, v154
	v_exp_f32_e32 v5, v5
	v_cmp_lt_f32_e32 vcc, s56, v12
	v_mul_f32_e32 v4, v155, v4
	s_nop 0
	v_cndmask_b32_e32 v6, 0, v4, vcc
	v_mul_f32_e32 v4, v155, v5
	v_sub_f32_e32 v5, v14, v154
	v_cmp_lt_f32_e32 vcc, s56, v13
	v_exp_f32_e32 v5, v5
	s_nop 0
	v_cndmask_b32_e32 v9, 0, v4, vcc
	v_sub_f32_e32 v4, v15, v154
	v_exp_f32_e32 v4, v4
	v_mul_f32_e32 v5, v155, v5
	v_cmp_lt_f32_e32 vcc, s56, v14
	v_mul_f32_e32 v4, v155, v4
	s_nop 0
	v_cndmask_b32_e32 v11, 0, v5, vcc
	v_cmp_lt_f32_e32 vcc, s56, v15
	s_nop 1
	v_cndmask_b32_e32 v13, 0, v4, vcc
	v_add_f32_e32 v4, v6, v9
	v_add_f32_e32 v4, v11, v4
	v_add_f32_e32 v4, v13, v4
	v_mov_b32_e32 v7, v13
	s_nop 0
	v_add_f32_dpp v4, v4, v4 quad_perm:[1,0,3,2] row_mask:0xf bank_mask:0xf
	v_add_f32_dpp v7, v7, v7 quad_perm:[1,0,3,2] row_mask:0xf bank_mask:0xf
	s_nop 0
	v_add_f32_dpp v4, v4, v4 quad_perm:[2,3,0,1] row_mask:0xf bank_mask:0xf
	v_add_f32_dpp v7, v7, v7 quad_perm:[2,3,0,1] row_mask:0xf bank_mask:0xf
	s_and_saveexec_b64 s[0:1], s[6:7]
	s_cbranch_execz .LBB0_706
	v_add_u32_e32 v5, 24, v70
	ds_write2st64_b32 v5, v4, v7 offset1:64
; DI void nsa_attn_phase(int wv, const P& p_, LAS unsigned char* lds) {
;     ...
;         for (int sub = 0; sub < 2; ++sub) {
; #pragma unroll
;           for (int reg = 0; reg < 16; ++reg) { const float v = s[sub][reg]; s[sub][reg] = v > -1e29f ? __builtin_amdgcn_exp2f(v - m) * inv : 0.f; }
; #pragma unroll
;           for (int lg = 0; lg < 4; ++lg) { float G = s[sub][4 * lg] + s[sub][4 * lg + 1] + s[sub][4 * lg + 2] + s[sub][4 * lg + 3], Lv = s[sub][4 * lg + 3];
;             G += __shfl_xor(G, 1); G += __shfl_xor(G, 2); Lv += __shfl_xor(Lv, 1); Lv += __shfl_xor(Lv, 2);
;             if (hd == 0) { gp[8 * sub + 2 * lg] = G; gp[4096 + 8 * sub + 2 * lg] = Lv; } }
.LBB0_706:
	s_or_b64 exec, exec, s[0:1]
	v_sub_f32_e32 v4, v16, v154
	v_exp_f32_e32 v4, v4
	s_waitcnt lgkmcnt(1)
	v_sub_f32_e32 v5, v17, v154
	v_exp_f32_e32 v5, v5
	v_sub_f32_e32 v7, v18, v154
	v_exp_f32_e32 v7, v7
	s_waitcnt lgkmcnt(0)
	v_sub_f32_e32 v8, v19, v154
	v_exp_f32_e32 v8, v8
	v_mul_f32_e32 v4, v155, v4
	v_cmp_lt_f32_e32 vcc, s56, v16
	v_mul_f32_e32 v5, v155, v5
	v_mul_f32_e32 v7, v155, v7
	v_cndmask_b32_e32 v4, 0, v4, vcc
	v_cmp_lt_f32_e32 vcc, s56, v17
	v_mul_f32_e32 v8, v155, v8
	s_nop 0
	v_cndmask_b32_e32 v5, 0, v5, vcc
	v_cmp_lt_f32_e32 vcc, s56, v18
	v_add_f32_e32 v10, v4, v5
	s_nop 0
	v_cndmask_b32_e32 v7, 0, v7, vcc
	v_cmp_lt_f32_e32 vcc, s56, v19
	v_add_f32_e32 v10, v7, v10
	s_nop 0
	v_cndmask_b32_e32 v8, 0, v8, vcc
	v_add_f32_e32 v10, v8, v10
	v_mov_b32_e32 v14, v8
	s_nop 0
	v_add_f32_dpp v10, v10, v10 quad_perm:[1,0,3,2] row_mask:0xf bank_mask:0xf
	v_add_f32_dpp v14, v14, v14 quad_perm:[1,0,3,2] row_mask:0xf bank_mask:0xf
	s_nop 0
	v_add_f32_dpp v10, v10, v10 quad_perm:[2,3,0,1] row_mask:0xf bank_mask:0xf
	v_add_f32_dpp v14, v14, v14 quad_perm:[2,3,0,1] row_mask:0xf bank_mask:0xf
	s_and_saveexec_b64 s[0:1], s[6:7]
	s_cbranch_execz .LBB0_708
	v_add_u32_e32 v12, 32, v70
	ds_write2st64_b32 v12, v10, v14 offset1:64
.LBB0_708:
	s_or_b64 exec, exec, s[0:1]
	v_sub_f32_e32 v10, v20, v154
	v_exp_f32_e32 v10, v10
	s_waitcnt lgkmcnt(1)
	v_sub_f32_e32 v12, v21, v154
	v_exp_f32_e32 v12, v12
	v_cmp_lt_f32_e32 vcc, s56, v20
	v_mul_f32_e32 v10, v155, v10
	s_nop 0
	v_cndmask_b32_e32 v16, 0, v10, vcc
	v_mul_f32_e32 v10, v155, v12
	v_sub_f32_e32 v12, v22, v154
	v_cmp_lt_f32_e32 vcc, s56, v21
	v_exp_f32_e32 v12, v12
	s_nop 0
	v_cndmask_b32_e32 v17, 0, v10, vcc
	v_sub_f32_e32 v10, v23, v154
	v_exp_f32_e32 v10, v10
	v_mul_f32_e32 v12, v155, v12
	v_cmp_lt_f32_e32 vcc, s56, v22
	v_mul_f32_e32 v10, v155, v10
	s_nop 0
	v_cndmask_b32_e32 v18, 0, v12, vcc
	v_cmp_lt_f32_e32 vcc, s56, v23
	s_nop 1
	v_cndmask_b32_e32 v19, 0, v10, vcc
	v_add_f32_e32 v10, v16, v17
	v_add_f32_e32 v10, v18, v10
	v_add_f32_e32 v10, v19, v10
	v_mov_b32_e32 v14, v19
	s_nop 0
	v_add_f32_dpp v10, v10, v10 quad_perm:[1,0,3,2] row_mask:0xf bank_mask:0xf
	v_add_f32_dpp v14, v14, v14 quad_perm:[1,0,3,2] row_mask:0xf bank_mask:0xf
	s_nop 0
	v_add_f32_dpp v10, v10, v10 quad_perm:[2,3,0,1] row_mask:0xf bank_mask:0xf
	v_add_f32_dpp v14, v14, v14 quad_perm:[2,3,0,1] row_mask:0xf bank_mask:0xf
	s_and_saveexec_b64 s[0:1], s[6:7]
	s_cbranch_execz .LBB0_710
	v_add_u32_e32 v12, 40, v70
	ds_write2st64_b32 v12, v10, v14 offset1:64
.LBB0_710:
	s_or_b64 exec, exec, s[0:1]
	v_sub_f32_e32 v10, v24, v154
	v_exp_f32_e32 v10, v10
	s_waitcnt lgkmcnt(1)
	v_sub_f32_e32 v12, v25, v154
	v_exp_f32_e32 v12, v12
	v_sub_f32_e32 v14, v26, v154
	v_exp_f32_e32 v14, v14
	s_waitcnt lgkmcnt(0)
	v_sub_f32_e32 v15, v27, v154
	v_exp_f32_e32 v15, v15
	v_mul_f32_e32 v10, v155, v10
	v_cmp_lt_f32_e32 vcc, s56, v24
	v_mul_f32_e32 v12, v155, v12
	v_mul_f32_e32 v14, v155, v14
	v_cndmask_b32_e32 v10, 0, v10, vcc
	v_cmp_lt_f32_e32 vcc, s56, v25
	v_mul_f32_e32 v15, v155, v15
	s_nop 0
	v_cndmask_b32_e32 v12, 0, v12, vcc
	v_cmp_lt_f32_e32 vcc, s56, v26
	v_add_f32_e32 v20, v10, v12
	s_nop 0
	v_cndmask_b32_e32 v14, 0, v14, vcc
	v_cmp_lt_f32_e32 vcc, s56, v27
	v_add_f32_e32 v20, v14, v20
	s_nop 0
	v_cndmask_b32_e32 v15, 0, v15, vcc
	v_add_f32_e32 v20, v15, v20
	v_mov_b32_e32 v22, v15
	s_nop 0
	v_add_f32_dpp v20, v20, v20 quad_perm:[1,0,3,2] row_mask:0xf bank_mask:0xf
	v_add_f32_dpp v22, v22, v22 quad_perm:[1,0,3,2] row_mask:0xf bank_mask:0xf
	s_nop 0
	v_add_f32_dpp v20, v20, v20 quad_perm:[2,3,0,1] row_mask:0xf bank_mask:0xf
	v_add_f32_dpp v22, v22, v22 quad_perm:[2,3,0,1] row_mask:0xf bank_mask:0xf
	s_and_saveexec_b64 s[0:1], s[6:7]
	s_cbranch_execz .LBB0_712
	v_add_u32_e32 v21, 48, v70
	ds_write2st64_b32 v21, v20, v22 offset1:64
.LBB0_712:
	s_or_b64 exec, exec, s[0:1]
	v_sub_f32_e32 v20, v28, v154
	v_exp_f32_e32 v20, v20
	s_waitcnt lgkmcnt(1)
	v_sub_f32_e32 v21, v29, v154
	v_exp_f32_e32 v21, v21
	v_sub_f32_e32 v22, v30, v154
	v_exp_f32_e32 v22, v22
	s_waitcnt lgkmcnt(0)
	v_sub_f32_e32 v23, v31, v154
	v_exp_f32_e32 v23, v23
	v_mul_f32_e32 v20, v155, v20
	v_cmp_lt_f32_e32 vcc, s56, v28
	v_mul_f32_e32 v21, v155, v21
	v_mul_f32_e32 v22, v155, v22
	v_cndmask_b32_e32 v20, 0, v20, vcc
	v_cmp_lt_f32_e32 vcc, s56, v29
	v_mul_f32_e32 v23, v155, v23
	s_nop 0
	v_cndmask_b32_e32 v21, 0, v21, vcc
	v_cmp_lt_f32_e32 vcc, s56, v30
	v_add_f32_e32 v24, v20, v21
	s_nop 0
	v_cndmask_b32_e32 v22, 0, v22, vcc
	v_cmp_lt_f32_e32 vcc, s56, v31
	v_add_f32_e32 v24, v22, v24
	s_nop 0
	v_cndmask_b32_e32 v23, 0, v23, vcc
	v_add_f32_e32 v24, v23, v24
	v_mov_b32_e32 v26, v23
	s_nop 0
	v_add_f32_dpp v24, v24, v24 quad_perm:[1,0,3,2] row_mask:0xf bank_mask:0xf
	v_add_f32_dpp v26, v26, v26 quad_perm:[1,0,3,2] row_mask:0xf bank_mask:0xf
	s_nop 0
	v_add_f32_dpp v24, v24, v24 quad_perm:[2,3,0,1] row_mask:0xf bank_mask:0xf
	v_add_f32_dpp v26, v26, v26 quad_perm:[2,3,0,1] row_mask:0xf bank_mask:0xf
	s_and_saveexec_b64 s[0:1], s[6:7]
	s_cbranch_execz .LBB0_693
	v_add_u32_e32 v25, 56, v70
	ds_write2st64_b32 v25, v24, v26 offset1:64
	s_branch .LBB0_693

; DI int crow(int reg, int h) { return (reg & 3) + 8 * (reg >> 2) + 4 * h; }
; DI void attn_logits(f32x16 (&s)[2], int t, int tw, int nt, int h, int base, int stride, int dmax, bool ok, const LAS float* btl) {
;     ...
;       for (int reg = 0; reg < 16; ++reg) {
;         const int kk = sub * 32 + crow(reg, h); const int d = t - (base + kk * stride);
;         const bool valid = (d >= 0) && (d < dmax) && ok;
;         const int di = d < 0 ? 0 : (d > 128 ? 128 : d);
;         const float bsv = btl[di];
;         const float x = s[sub][reg] * QK_SCALE2 + bsv;
; DI void attn_tile(const LAS bf16_t* Ks, const LAS bf16_t* Vt, int vstride, const bf16x8 (&qf)[4], f32x16 (&O)[2], float& m, float& l,
;                   int t, int tw, int nt, int r, int h, int base, int stride, int dmax, bool ok, const LAS float* btl) {
;     ...
;   if (dmin >= 128 && dmaxw < dmax) {
;     const float cl = ok ? QK_SCALE2 : 0.f, bl = ok ? btl[128] : -1e30f;
;     float mr = -3e38f;
; #pragma unroll
;     for (int sub = 0; sub < 2; ++sub)
; #pragma unroll
;       for (int reg = 0; reg < 16; ++reg) mr = fmaxf(mr, s[sub][reg]);
;     float mx = mr * cl + bl; mx = fmaxf(mx, __shfl_xor(mx, 32));
;     mn = fmaxf(m, mx);
;     const float off = bl - mn;
; #pragma unroll
;     for (int sub = 0; sub < 2; ++sub)
; #pragma unroll
;       for (int reg = 0; reg < 16; ++reg) { const float e = __builtin_amdgcn_exp2f(s[sub][reg] * cl + off); s[sub][reg] = e; ls += e; }
.LBB0_779:
	v_mov_b32_e32 v0, 0xf149f2ca
	s_mov_b32 s8, 0xff61b1e6
	v_cndmask_b32_e64 v0, v0, v224, s[6:7]
	v_max3_f32 v1, v82, s8, v83
	v_max3_f32 v1, v1, v84, v85
	v_max3_f32 v1, v1, v86, v87
	v_max3_f32 v1, v1, v88, v89
	v_max3_f32 v1, v1, v90, v91
	v_max3_f32 v1, v1, v92, v93
	v_max3_f32 v1, v1, v94, v95
	v_max3_f32 v1, v1, v96, v97
	v_max3_f32 v1, v1, v66, v67
	v_max3_f32 v1, v1, v68, v69
	v_max3_f32 v1, v1, v70, v71
	v_max3_f32 v1, v1, v72, v73
	v_max3_f32 v1, v1, v74, v75
	v_max3_f32 v1, v1, v76, v77
	v_max3_f32 v1, v1, v78, v79
	v_cndmask_b32_e64 v172, 0, v242, s[6:7]
	v_max3_f32 v1, v1, v80, v81
	s_waitcnt lgkmcnt(0)
	v_fma_f32 v1, v172, v1, v0
	v_mov_b32_e32 v2, v1
	s_nop 1
	v_permlane32_swap_b32_e32 v1, v2
	v_max3_f32 v139, v171, v1, v2
	v_sub_f32_e32 v174, v0, v139
	s_nop 0
	v_pk_fma_f32 v[0:1], v[82:83], v[172:173], v[174:175] op_sel_hi:[1,0,0]
	v_pk_fma_f32 v[2:3], v[84:85], v[172:173], v[174:175] op_sel_hi:[1,0,0]
	v_pk_fma_f32 v[4:5], v[86:87], v[172:173], v[174:175] op_sel_hi:[1,0,0]
	v_pk_fma_f32 v[6:7], v[88:89], v[172:173], v[174:175] op_sel_hi:[1,0,0]
	v_pk_fma_f32 v[8:9], v[90:91], v[172:173], v[174:175] op_sel_hi:[1,0,0]
	v_pk_fma_f32 v[10:11], v[92:93], v[172:173], v[174:175] op_sel_hi:[1,0,0]
	v_pk_fma_f32 v[12:13], v[94:95], v[172:173], v[174:175] op_sel_hi:[1,0,0]
	v_pk_fma_f32 v[14:15], v[96:97], v[172:173], v[174:175] op_sel_hi:[1,0,0]
	v_pk_fma_f32 v[16:17], v[66:67], v[172:173], v[174:175] op_sel_hi:[1,0,0]
	v_pk_fma_f32 v[18:19], v[68:69], v[172:173], v[174:175] op_sel_hi:[1,0,0]
	v_pk_fma_f32 v[20:21], v[70:71], v[172:173], v[174:175] op_sel_hi:[1,0,0]
	v_pk_fma_f32 v[22:23], v[72:73], v[172:173], v[174:175] op_sel_hi:[1,0,0]
	v_pk_fma_f32 v[24:25], v[74:75], v[172:173], v[174:175] op_sel_hi:[1,0,0]
	v_pk_fma_f32 v[26:27], v[76:77], v[172:173], v[174:175] op_sel_hi:[1,0,0]
	v_pk_fma_f32 v[28:29], v[78:79], v[172:173], v[174:175] op_sel_hi:[1,0,0]
	v_pk_fma_f32 v[30:31], v[80:81], v[172:173], v[174:175] op_sel_hi:[1,0,0]
	v_exp_f32_e32 v0, v0
	v_exp_f32_e32 v1, v1
	v_exp_f32_e32 v2, v2
	v_exp_f32_e32 v3, v3
	v_exp_f32_e32 v4, v4
	v_exp_f32_e32 v5, v5
	v_exp_f32_e32 v6, v6
	v_exp_f32_e32 v7, v7
	v_exp_f32_e32 v8, v8
	v_exp_f32_e32 v9, v9
	v_exp_f32_e32 v10, v10
	v_exp_f32_e32 v11, v11
	v_exp_f32_e32 v12, v12
	v_exp_f32_e32 v13, v13
	v_exp_f32_e32 v14, v14
	v_exp_f32_e32 v15, v15
	v_exp_f32_e32 v16, v16
	v_exp_f32_e32 v17, v17
	v_exp_f32_e32 v18, v18
	v_exp_f32_e32 v19, v19
	v_exp_f32_e32 v20, v20
	v_exp_f32_e32 v21, v21
	v_exp_f32_e32 v22, v22
	v_exp_f32_e32 v23, v23
	v_exp_f32_e32 v24, v24
	v_exp_f32_e32 v25, v25
	v_exp_f32_e32 v26, v26
	v_exp_f32_e32 v27, v27
	v_exp_f32_e32 v28, v28
	v_exp_f32_e32 v29, v29
	v_exp_f32_e32 v30, v30
	v_mov_b32_e32 v141, v31
	v_pk_add_f32 v[176:177], v[0:1], v[2:3]
	v_pk_add_f32 v[178:179], v[4:5], v[6:7]
	v_pk_add_f32 v[176:177], v[176:177], v[8:9]
	v_pk_add_f32 v[178:179], v[178:179], v[10:11]
	v_pk_add_f32 v[176:177], v[176:177], v[12:13]
	v_pk_add_f32 v[178:179], v[178:179], v[14:15]
	v_pk_add_f32 v[176:177], v[176:177], v[16:17]
	v_pk_add_f32 v[178:179], v[178:179], v[18:19]
	v_pk_add_f32 v[176:177], v[176:177], v[20:21]
	v_pk_add_f32 v[178:179], v[178:179], v[22:23]
	v_pk_add_f32 v[176:177], v[176:177], v[24:25]
	v_pk_add_f32 v[178:179], v[178:179], v[26:27]
	v_pk_add_f32 v[176:177], v[176:177], v[28:29]
	s_nop 0
	v_pk_add_f32 v[176:177], v[176:177], v[178:179]
	s_nop 0
	v_add_f32_e32 v140, v176, v177
	v_add_f32_e32 v140, v30, v140
	s_branch .LBB0_777
.Lsel_near_new:
	v_subrev_u32_e32 v172, s10, v147
	v_sub_u32_e32 v172, v172, v144
	v_lshl_add_u32 v184, v172, 2, v158
	v_add_u32_e32 v185, -4, v158
	v_add_u32_e32 v186, 0x200, v158
	v_cndmask_b32_e64 v186, v185, v186, s[6:7]
	v_med3_i32 v172, v184, v185, v186
	v_subrev_u32_e32 v173, 4, v184
	v_med3_i32 v173, v173, v185, v186
	v_subrev_u32_e32 v174, 8, v184
	v_med3_i32 v174, v174, v185, v186
	v_subrev_u32_e32 v175, 12, v184
	v_med3_i32 v175, v175, v185, v186
	v_subrev_u32_e32 v180, 32, v184
	v_med3_i32 v180, v180, v185, v186
	v_subrev_u32_e32 v181, 36, v184
	v_med3_i32 v181, v181, v185, v186
	v_subrev_u32_e32 v182, 40, v184
	v_med3_i32 v182, v182, v185, v186
	v_subrev_u32_e32 v183, 44, v184
	v_med3_i32 v183, v183, v185, v186
	ds_read_b32 v0, v172
	ds_read_b32 v1, v173
	ds_read_b32 v2, v174
	ds_read_b32 v3, v175
	ds_read_b32 v4, v180
	ds_read_b32 v5, v181
	ds_read_b32 v6, v182
	ds_read_b32 v7, v183
	v_subrev_u32_e32 v172, 64, v184
	v_med3_i32 v172, v172, v185, v186
	v_subrev_u32_e32 v173, 68, v184
	v_med3_i32 v173, v173, v185, v186
	v_subrev_u32_e32 v174, 72, v184
	v_med3_i32 v174, v174, v185, v186
	v_subrev_u32_e32 v175, 76, v184
	v_med3_i32 v175, v175, v185, v186
	v_subrev_u32_e32 v180, 96, v184
	v_med3_i32 v180, v180, v185, v186
	v_subrev_u32_e32 v181, 100, v184
	v_med3_i32 v181, v181, v185, v186
	v_subrev_u32_e32 v182, 104, v184
	v_med3_i32 v182, v182, v185, v186
	v_subrev_u32_e32 v183, 108, v184
	v_med3_i32 v183, v183, v185, v186
	ds_read_b32 v8, v172
	ds_read_b32 v9, v173
	ds_read_b32 v10, v174
	ds_read_b32 v11, v175
	ds_read_b32 v12, v180
	ds_read_b32 v13, v181
	ds_read_b32 v14, v182
	ds_read_b32 v15, v183
	s_waitcnt lgkmcnt(8)
; DI int crow(int reg, int h) { return (reg & 3) + 8 * (reg >> 2) + 4 * h; }
; DI void attn_logits(f32x16 (&s)[2], int t, int tw, int nt, int h, int base, int stride, int dmax, bool ok, const LAS float* btl) {
;     ...
;       for (int reg = 0; reg < 16; ++reg) {
;         const int kk = sub * 32 + crow(reg, h); const int d = t - (base + kk * stride);
;         const bool valid = (d >= 0) && (d < dmax) && ok;
;         const int di = d < 0 ? 0 : (d > 128 ? 128 : d);
;         const float bsv = btl[di];
;         const float x = s[sub][reg] * QK_SCALE2 + bsv;
;         s[sub][reg] = valid ? x : -1e30f;
;       }
; DI void attn_tile(const LAS bf16_t* Ks, const LAS bf16_t* Vt, int vstride, const bf16x8 (&qf)[4], f32x16 (&O)[2], float& m, float& l,
;                   int t, int tw, int nt, int r, int h, int base, int stride, int dmax, bool ok, const LAS float* btl) {
;     ...
;     float mx = -1e30f;
; #pragma unroll
;     for (int sub = 0; sub < 2; ++sub)
; #pragma unroll
;       for (int reg = 0; reg < 16; ++reg) mx = fmaxf(mx, s[sub][reg]);
;     mx = fmaxf(mx, __shfl_xor(mx, 32));
;     mn = fmaxf(m, mx);
; #pragma unroll
;     for (int sub = 0; sub < 2; ++sub)
; #pragma unroll
;       for (int reg = 0; reg < 16; ++reg) { const float e = __builtin_amdgcn_exp2f(s[sub][reg] - mn); s[sub][reg] = e; ls += e; }
	v_fmac_f32_e32 v0, 0x3e38aa3b, v82
	v_fmac_f32_e32 v1, 0x3e38aa3b, v83
	v_fmac_f32_e32 v2, 0x3e38aa3b, v84
	v_fmac_f32_e32 v3, 0x3e38aa3b, v85
	v_fmac_f32_e32 v4, 0x3e38aa3b, v86
	v_fmac_f32_e32 v5, 0x3e38aa3b, v87
	v_fmac_f32_e32 v6, 0x3e38aa3b, v88
	v_fmac_f32_e32 v7, 0x3e38aa3b, v89
	v_subrev_u32_e32 v172, 128, v184
	v_med3_i32 v172, v172, v185, v186
	v_subrev_u32_e32 v173, 132, v184
	v_med3_i32 v173, v173, v185, v186
	v_subrev_u32_e32 v174, 136, v184
	v_med3_i32 v174, v174, v185, v186
	v_subrev_u32_e32 v175, 140, v184
	v_med3_i32 v175, v175, v185, v186
	v_subrev_u32_e32 v180, 160, v184
	v_med3_i32 v180, v180, v185, v186
	v_subrev_u32_e32 v181, 164, v184
	v_med3_i32 v181, v181, v185, v186
	v_subrev_u32_e32 v182, 168, v184
	v_med3_i32 v182, v182, v185, v186
	v_subrev_u32_e32 v183, 172, v184
	v_med3_i32 v183, v183, v185, v186
	ds_read_b32 v16, v172
	ds_read_b32 v17, v173
	ds_read_b32 v18, v174
	ds_read_b32 v19, v175
	ds_read_b32 v20, v180
	ds_read_b32 v21, v181
	ds_read_b32 v22, v182
	ds_read_b32 v23, v183
	s_waitcnt lgkmcnt(8)
	v_fmac_f32_e32 v8, 0x3e38aa3b, v90
	v_fmac_f32_e32 v9, 0x3e38aa3b, v91
	v_fmac_f32_e32 v10, 0x3e38aa3b, v92
	v_fmac_f32_e32 v11, 0x3e38aa3b, v93
	v_fmac_f32_e32 v12, 0x3e38aa3b, v94
	v_fmac_f32_e32 v13, 0x3e38aa3b, v95
	v_fmac_f32_e32 v14, 0x3e38aa3b, v96
	v_fmac_f32_e32 v15, 0x3e38aa3b, v97
	v_subrev_u32_e32 v172, 192, v184
	v_med3_i32 v172, v172, v185, v186
	v_subrev_u32_e32 v173, 196, v184
	v_med3_i32 v173, v173, v185, v186
	v_subrev_u32_e32 v174, 200, v184
	v_med3_i32 v174, v174, v185, v186
	v_subrev_u32_e32 v175, 204, v184
	v_med3_i32 v175, v175, v185, v186
	v_subrev_u32_e32 v180, 224, v184
	v_med3_i32 v180, v180, v185, v186
	v_subrev_u32_e32 v181, 228, v184
	v_med3_i32 v181, v181, v185, v186
	v_subrev_u32_e32 v182, 232, v184
	v_med3_i32 v182, v182, v185, v186
	v_subrev_u32_e32 v183, 236, v184
	v_med3_i32 v183, v183, v185, v186
	ds_read_b32 v24, v172
	ds_read_b32 v25, v173
	ds_read_b32 v26, v174
	ds_read_b32 v27, v175
	ds_read_b32 v28, v180
	ds_read_b32 v29, v181
	ds_read_b32 v30, v182
	ds_read_b32 v31, v183
	s_waitcnt lgkmcnt(8)
	v_fmac_f32_e32 v16, 0x3e38aa3b, v66
	v_fmac_f32_e32 v17, 0x3e38aa3b, v67
	v_fmac_f32_e32 v18, 0x3e38aa3b, v68
	v_fmac_f32_e32 v19, 0x3e38aa3b, v69
	v_fmac_f32_e32 v20, 0x3e38aa3b, v70
	v_fmac_f32_e32 v21, 0x3e38aa3b, v71
	v_fmac_f32_e32 v22, 0x3e38aa3b, v72
	v_fmac_f32_e32 v23, 0x3e38aa3b, v73
	s_waitcnt lgkmcnt(0)
	v_fmac_f32_e32 v24, 0x3e38aa3b, v74
	v_fmac_f32_e32 v25, 0x3e38aa3b, v75
	v_fmac_f32_e32 v26, 0x3e38aa3b, v76
	v_fmac_f32_e32 v27, 0x3e38aa3b, v77
	v_fmac_f32_e32 v28, 0x3e38aa3b, v78
	v_fmac_f32_e32 v29, 0x3e38aa3b, v79
	v_fmac_f32_e32 v30, 0x3e38aa3b, v80
	v_fmac_f32_e32 v31, 0x3e38aa3b, v81
	v_max3_f32 v172, v0, s44, v1
	v_max3_f32 v172, v172, v2, v3
	v_max3_f32 v172, v172, v4, v5
	v_max3_f32 v172, v172, v6, v7
	v_max3_f32 v172, v172, v8, v9
	v_max3_f32 v172, v172, v10, v11
	v_max3_f32 v172, v172, v12, v13
	v_max3_f32 v172, v172, v14, v15
	v_max3_f32 v172, v172, v16, v17
	v_max3_f32 v172, v172, v18, v19
	v_max3_f32 v172, v172, v20, v21
	v_max3_f32 v172, v172, v22, v23
	v_max3_f32 v172, v172, v24, v25
	v_max3_f32 v172, v172, v26, v27
	v_max3_f32 v172, v172, v28, v29
	v_max3_f32 v172, v172, v30, v31
	v_mov_b32_e32 v173, v172
	s_nop 1
	v_permlane32_swap_b32_e32 v172, v173
	v_max3_f32 v139, v171, v172, v173
	s_nop 0
	v_pk_add_f32 v[0:1], v[0:1], v[138:139] op_sel:[0,1] op_sel_hi:[1,1] neg_lo:[0,1] neg_hi:[0,1]
	v_pk_add_f32 v[2:3], v[2:3], v[138:139] op_sel:[0,1] op_sel_hi:[1,1] neg_lo:[0,1] neg_hi:[0,1]
	v_pk_add_f32 v[4:5], v[4:5], v[138:139] op_sel:[0,1] op_sel_hi:[1,1] neg_lo:[0,1] neg_hi:[0,1]
	v_pk_add_f32 v[6:7], v[6:7], v[138:139] op_sel:[0,1] op_sel_hi:[1,1] neg_lo:[0,1] neg_hi:[0,1]
	v_pk_add_f32 v[8:9], v[8:9], v[138:139] op_sel:[0,1] op_sel_hi:[1,1] neg_lo:[0,1] neg_hi:[0,1]
	v_pk_add_f32 v[10:11], v[10:11], v[138:139] op_sel:[0,1] op_sel_hi:[1,1] neg_lo:[0,1] neg_hi:[0,1]
	v_pk_add_f32 v[12:13], v[12:13], v[138:139] op_sel:[0,1] op_sel_hi:[1,1] neg_lo:[0,1] neg_hi:[0,1]
	v_pk_add_f32 v[14:15], v[14:15], v[138:139] op_sel:[0,1] op_sel_hi:[1,1] neg_lo:[0,1] neg_hi:[0,1]
	v_pk_add_f32 v[16:17], v[16:17], v[138:139] op_sel:[0,1] op_sel_hi:[1,1] neg_lo:[0,1] neg_hi:[0,1]
	v_pk_add_f32 v[18:19], v[18:19], v[138:139] op_sel:[0,1] op_sel_hi:[1,1] neg_lo:[0,1] neg_hi:[0,1]
	v_pk_add_f32 v[20:21], v[20:21], v[138:139] op_sel:[0,1] op_sel_hi:[1,1] neg_lo:[0,1] neg_hi:[0,1]
	v_pk_add_f32 v[22:23], v[22:23], v[138:139] op_sel:[0,1] op_sel_hi:[1,1] neg_lo:[0,1] neg_hi:[0,1]
	v_pk_add_f32 v[24:25], v[24:25], v[138:139] op_sel:[0,1] op_sel_hi:[1,1] neg_lo:[0,1] neg_hi:[0,1]
	v_pk_add_f32 v[26:27], v[26:27], v[138:139] op_sel:[0,1] op_sel_hi:[1,1] neg_lo:[0,1] neg_hi:[0,1]
	v_pk_add_f32 v[28:29], v[28:29], v[138:139] op_sel:[0,1] op_sel_hi:[1,1] neg_lo:[0,1] neg_hi:[0,1]
	v_pk_add_f32 v[30:31], v[30:31], v[138:139] op_sel:[0,1] op_sel_hi:[1,1] neg_lo:[0,1] neg_hi:[0,1]
	v_exp_f32_e32 v0, v0
	v_exp_f32_e32 v1, v1
	v_exp_f32_e32 v2, v2
	v_exp_f32_e32 v3, v3
	v_exp_f32_e32 v4, v4
	v_exp_f32_e32 v5, v5
	v_exp_f32_e32 v6, v6
	v_exp_f32_e32 v7, v7
	v_exp_f32_e32 v8, v8
	v_exp_f32_e32 v9, v9
	v_exp_f32_e32 v10, v10
	v_exp_f32_e32 v11, v11
	v_exp_f32_e32 v12, v12
	v_exp_f32_e32 v13, v13
	v_exp_f32_e32 v14, v14
	v_exp_f32_e32 v15, v15
	v_exp_f32_e32 v16, v16
	v_exp_f32_e32 v17, v17
	v_exp_f32_e32 v18, v18
	v_exp_f32_e32 v19, v19
	v_exp_f32_e32 v20, v20
	v_exp_f32_e32 v21, v21
	v_exp_f32_e32 v22, v22
	v_exp_f32_e32 v23, v23
	v_exp_f32_e32 v24, v24
	v_exp_f32_e32 v25, v25
	v_exp_f32_e32 v26, v26
	v_exp_f32_e32 v27, v27
	v_exp_f32_e32 v28, v28
	v_exp_f32_e32 v29, v29
	v_exp_f32_e32 v30, v30
	v_mov_b32_e32 v141, v31
	v_pk_add_f32 v[176:177], v[0:1], v[2:3]
	v_pk_add_f32 v[178:179], v[4:5], v[6:7]
	v_pk_add_f32 v[176:177], v[176:177], v[8:9]
	v_pk_add_f32 v[178:179], v[178:179], v[10:11]
	v_pk_add_f32 v[176:177], v[176:177], v[12:13]
	v_pk_add_f32 v[178:179], v[178:179], v[14:15]
	v_pk_add_f32 v[176:177], v[176:177], v[16:17]
	v_pk_add_f32 v[178:179], v[178:179], v[18:19]
	v_pk_add_f32 v[176:177], v[176:177], v[20:21]
	v_pk_add_f32 v[178:179], v[178:179], v[22:23]
	v_pk_add_f32 v[176:177], v[176:177], v[24:25]
	v_pk_add_f32 v[178:179], v[178:179], v[26:27]
	v_pk_add_f32 v[176:177], v[176:177], v[28:29]
	s_nop 0
	v_pk_add_f32 v[176:177], v[176:177], v[178:179]
	s_nop 0
	v_add_f32_e32 v140, v176, v177
	v_add_f32_e32 v140, v30, v140
	s_branch .LBB0_777

; DI int crow(int reg, int h) { return (reg & 3) + 8 * (reg >> 2) + 4 * h; }
; DI void attn_logits(f32x16 (&s)[2], int t, int tw, int nt, int h, int base, int stride, int dmax, bool ok, const LAS float* btl) {
;     ...
;       for (int reg = 0; reg < 16; ++reg) {
;         const int kk = sub * 32 + crow(reg, h); const int d = t - (base + kk * stride);
;         const bool valid = (d >= 0) && (d < dmax) && ok;
;         const int di = d < 0 ? 0 : (d > 128 ? 128 : d);
;         const float bsv = btl[di];
;         const float x = s[sub][reg] * QK_SCALE2 + bsv;
.Lwin_near_new:
	v_add3_u32 v33, v157, s15, 63
	v_sub_u32_e32 v33, v33, v68
	v_lshl_add_u32 v214, v33, 2, v158
	v_add_u32_e32 v215, -4, v158
	v_add_u32_e32 v154, 0x200, v158
	v_med3_i32 v33, v214, v215, v154
	v_subrev_u32_e32 v150, 4, v214
	v_med3_i32 v150, v150, v215, v154
	v_subrev_u32_e32 v153, 8, v214
	v_med3_i32 v153, v153, v215, v154
	v_subrev_u32_e32 v193, 12, v214
	v_med3_i32 v193, v193, v215, v154
	v_subrev_u32_e32 v202, 32, v214
	v_med3_i32 v202, v202, v215, v154
	v_subrev_u32_e32 v203, 36, v214
	v_med3_i32 v203, v203, v215, v154
	v_subrev_u32_e32 v204, 40, v214
	v_med3_i32 v204, v204, v215, v154
	v_subrev_u32_e32 v208, 44, v214
	v_med3_i32 v208, v208, v215, v154
	ds_read_b32 v205, v33
	ds_read_b32 v206, v150
	ds_read_b32 v207, v153
	ds_read_b32 v209, v193
	ds_read_b32 v210, v202
	ds_read_b32 v211, v203
	ds_read_b32 v212, v204
	ds_read_b32 v213, v208
	v_subrev_u32_e32 v33, 64, v214
	v_med3_i32 v33, v33, v215, v154
	v_subrev_u32_e32 v150, 68, v214
	v_med3_i32 v150, v150, v215, v154
	v_subrev_u32_e32 v153, 72, v214
	v_med3_i32 v153, v153, v215, v154
	v_subrev_u32_e32 v193, 76, v214
	v_med3_i32 v193, v193, v215, v154
	v_subrev_u32_e32 v202, 96, v214
	v_med3_i32 v202, v202, v215, v154
	v_subrev_u32_e32 v203, 100, v214
	v_med3_i32 v203, v203, v215, v154
	v_subrev_u32_e32 v204, 104, v214
	v_med3_i32 v204, v204, v215, v154
	v_subrev_u32_e32 v208, 108, v214
	v_med3_i32 v208, v208, v215, v154
	ds_read_b32 v171, v33
	ds_read_b32 v172, v150
	ds_read_b32 v173, v153
	ds_read_b32 v174, v193
	ds_read_b32 v176, v202
	ds_read_b32 v178, v203
	ds_read_b32 v181, v204
	ds_read_b32 v185, v208
	s_waitcnt lgkmcnt(8)
	v_fmac_f32_e32 v205, 0x3e38aa3b, v50
	v_fmac_f32_e32 v206, 0x3e38aa3b, v51
	v_fmac_f32_e32 v207, 0x3e38aa3b, v52
	v_fmac_f32_e32 v209, 0x3e38aa3b, v53
	v_fmac_f32_e32 v210, 0x3e38aa3b, v54
	v_fmac_f32_e32 v211, 0x3e38aa3b, v55
	v_fmac_f32_e32 v212, 0x3e38aa3b, v56
	v_fmac_f32_e32 v213, 0x3e38aa3b, v57
	v_subrev_u32_e32 v33, 128, v214
	v_med3_i32 v33, v33, v215, v154
	v_subrev_u32_e32 v150, 132, v214
	v_med3_i32 v150, v150, v215, v154
	v_subrev_u32_e32 v153, 136, v214
	v_med3_i32 v153, v153, v215, v154
	v_subrev_u32_e32 v193, 140, v214
	v_med3_i32 v193, v193, v215, v154
	v_subrev_u32_e32 v202, 160, v214
	v_med3_i32 v202, v202, v215, v154
	v_subrev_u32_e32 v203, 164, v214
	v_med3_i32 v203, v203, v215, v154
	v_subrev_u32_e32 v204, 168, v214
	v_med3_i32 v204, v204, v215, v154
	v_subrev_u32_e32 v208, 172, v214
	v_med3_i32 v208, v208, v215, v154
	ds_read_b32 v179, v33
	ds_read_b32 v182, v150
	ds_read_b32 v184, v153
	ds_read_b32 v186, v193
	ds_read_b32 v189, v202
	ds_read_b32 v190, v203
	ds_read_b32 v191, v204
	ds_read_b32 v192, v208
	s_waitcnt lgkmcnt(8)
	v_fmac_f32_e32 v171, 0x3e38aa3b, v58
	v_fmac_f32_e32 v172, 0x3e38aa3b, v59
	v_fmac_f32_e32 v173, 0x3e38aa3b, v60
	v_fmac_f32_e32 v174, 0x3e38aa3b, v61
	v_fmac_f32_e32 v176, 0x3e38aa3b, v62
	v_fmac_f32_e32 v178, 0x3e38aa3b, v63
	v_fmac_f32_e32 v181, 0x3e38aa3b, v64
	v_fmac_f32_e32 v185, 0x3e38aa3b, v65
	v_subrev_u32_e32 v33, 192, v214
	v_med3_i32 v33, v33, v215, v154
	v_subrev_u32_e32 v150, 196, v214
	v_med3_i32 v150, v150, v215, v154
	v_subrev_u32_e32 v153, 200, v214
	v_med3_i32 v153, v153, v215, v154
	v_subrev_u32_e32 v193, 204, v214
	v_med3_i32 v193, v193, v215, v154
	v_subrev_u32_e32 v202, 224, v214
	v_med3_i32 v202, v202, v215, v154
	v_subrev_u32_e32 v203, 228, v214
	v_med3_i32 v203, v203, v215, v154
	v_subrev_u32_e32 v204, 232, v214
	v_med3_i32 v204, v204, v215, v154
	v_subrev_u32_e32 v208, 236, v214
	v_med3_i32 v208, v208, v215, v154
	ds_read_b32 v175, v33
	ds_read_b32 v177, v150
	ds_read_b32 v180, v153
	ds_read_b32 v183, v193
	ds_read_b32 v187, v202
	ds_read_b32 v188, v203
	ds_read_b32 v152, v204
	ds_read_b32 v155, v208
	s_waitcnt lgkmcnt(8)
	v_fmac_f32_e32 v179, 0x3e38aa3b, v34
	v_fmac_f32_e32 v182, 0x3e38aa3b, v35
	v_fmac_f32_e32 v184, 0x3e38aa3b, v36
	v_fmac_f32_e32 v186, 0x3e38aa3b, v37
	v_fmac_f32_e32 v189, 0x3e38aa3b, v38
	v_fmac_f32_e32 v190, 0x3e38aa3b, v39
	v_fmac_f32_e32 v191, 0x3e38aa3b, v40
	v_fmac_f32_e32 v192, 0x3e38aa3b, v41
	s_waitcnt lgkmcnt(0)
; DI void attn_logits(f32x16 (&s)[2], int t, int tw, int nt, int h, int base, int stride, int dmax, bool ok, const LAS float* btl) {
;     ...
;         const float bsv = btl[di];
;         const float x = s[sub][reg] * QK_SCALE2 + bsv;
;         s[sub][reg] = valid ? x : -1e30f;
;       }
; DI void attn_tile(const LAS bf16_t* Ks, const LAS bf16_t* Vt, int vstride, const bf16x8 (&qf)[4], f32x16 (&O)[2], float& m, float& l,
;                   int t, int tw, int nt, int r, int h, int base, int stride, int dmax, bool ok, const LAS float* btl) {
;     ...
;     float mx = -1e30f;
; #pragma unroll
;     for (int sub = 0; sub < 2; ++sub)
; #pragma unroll
;       for (int reg = 0; reg < 16; ++reg) mx = fmaxf(mx, s[sub][reg]);
;     mx = fmaxf(mx, __shfl_xor(mx, 32));
;     mn = fmaxf(m, mx);
; #pragma unroll
;     for (int sub = 0; sub < 2; ++sub)
; #pragma unroll
;       for (int reg = 0; reg < 16; ++reg) { const float e = __builtin_amdgcn_exp2f(s[sub][reg] - mn); s[sub][reg] = e; ls += e; }
	v_fmac_f32_e32 v175, 0x3e38aa3b, v42
	v_fmac_f32_e32 v177, 0x3e38aa3b, v43
	v_fmac_f32_e32 v180, 0x3e38aa3b, v44
	v_fmac_f32_e32 v183, 0x3e38aa3b, v45
	v_fmac_f32_e32 v187, 0x3e38aa3b, v46
	v_fmac_f32_e32 v188, 0x3e38aa3b, v47
	v_fmac_f32_e32 v152, 0x3e38aa3b, v48
	v_fmac_f32_e32 v155, 0x3e38aa3b, v49
	v_max3_f32 v33, v205, s60, v206
	v_max3_f32 v33, v33, v207, v209
	v_max3_f32 v33, v33, v210, v211
	v_max3_f32 v33, v33, v212, v213
	v_max3_f32 v33, v33, v171, v172
	v_max3_f32 v33, v33, v173, v174
	v_max3_f32 v33, v33, v176, v178
	v_max3_f32 v33, v33, v181, v185
	v_max3_f32 v33, v33, v179, v182
	v_max3_f32 v33, v33, v184, v186
	v_max3_f32 v33, v33, v189, v190
	v_max3_f32 v33, v33, v191, v192
	v_max3_f32 v33, v33, v175, v177
	v_max3_f32 v33, v33, v180, v183
	v_max3_f32 v33, v33, v187, v188
	v_max3_f32 v33, v33, v152, v155
	v_mov_b32_e32 v150, v33
	s_nop 1
	v_permlane32_swap_b32_e32 v33, v150
	v_max3_f32 v151, v170, v33, v150
	s_nop 0
	v_pk_add_f32 v[172:173], v[172:173], v[150:151] op_sel:[0,1] op_sel_hi:[1,1] neg_lo:[0,1] neg_hi:[0,1]
	v_pk_add_f32 v[174:175], v[174:175], v[150:151] op_sel:[0,1] op_sel_hi:[1,1] neg_lo:[0,1] neg_hi:[0,1]
	v_pk_add_f32 v[176:177], v[176:177], v[150:151] op_sel:[0,1] op_sel_hi:[1,1] neg_lo:[0,1] neg_hi:[0,1]
	v_pk_add_f32 v[178:179], v[178:179], v[150:151] op_sel:[0,1] op_sel_hi:[1,1] neg_lo:[0,1] neg_hi:[0,1]
	v_pk_add_f32 v[180:181], v[180:181], v[150:151] op_sel:[0,1] op_sel_hi:[1,1] neg_lo:[0,1] neg_hi:[0,1]
	v_pk_add_f32 v[182:183], v[182:183], v[150:151] op_sel:[0,1] op_sel_hi:[1,1] neg_lo:[0,1] neg_hi:[0,1]
	v_pk_add_f32 v[184:185], v[184:185], v[150:151] op_sel:[0,1] op_sel_hi:[1,1] neg_lo:[0,1] neg_hi:[0,1]
	v_pk_add_f32 v[186:187], v[186:187], v[150:151] op_sel:[0,1] op_sel_hi:[1,1] neg_lo:[0,1] neg_hi:[0,1]
	v_pk_add_f32 v[188:189], v[188:189], v[150:151] op_sel:[0,1] op_sel_hi:[1,1] neg_lo:[0,1] neg_hi:[0,1]
	v_pk_add_f32 v[190:191], v[190:191], v[150:151] op_sel:[0,1] op_sel_hi:[1,1] neg_lo:[0,1] neg_hi:[0,1]
	v_pk_add_f32 v[206:207], v[206:207], v[150:151] op_sel:[0,1] op_sel_hi:[1,1] neg_lo:[0,1] neg_hi:[0,1]
	v_pk_add_f32 v[210:211], v[210:211], v[150:151] op_sel:[0,1] op_sel_hi:[1,1] neg_lo:[0,1] neg_hi:[0,1]
	v_pk_add_f32 v[212:213], v[212:213], v[150:151] op_sel:[0,1] op_sel_hi:[1,1] neg_lo:[0,1] neg_hi:[0,1]
	v_sub_f32_e32 v152, v152, v151
	v_sub_f32_e32 v155, v155, v151
	v_sub_f32_e32 v171, v171, v151
	v_sub_f32_e32 v192, v192, v151
	v_sub_f32_e32 v205, v205, v151
	v_sub_f32_e32 v209, v209, v151
	v_exp_f32_e32 v205, v205
	v_exp_f32_e32 v206, v206
	v_exp_f32_e32 v207, v207
	v_exp_f32_e32 v209, v209
	v_exp_f32_e32 v210, v210
	v_exp_f32_e32 v211, v211
	v_exp_f32_e32 v212, v212
	v_exp_f32_e32 v213, v213
	v_exp_f32_e32 v171, v171
	v_exp_f32_e32 v172, v172
	v_exp_f32_e32 v173, v173
	v_exp_f32_e32 v174, v174
	v_exp_f32_e32 v176, v176
	v_exp_f32_e32 v178, v178
	v_exp_f32_e32 v181, v181
	v_exp_f32_e32 v185, v185
	v_exp_f32_e32 v179, v179
	v_exp_f32_e32 v182, v182
	v_exp_f32_e32 v184, v184
	v_exp_f32_e32 v186, v186
	v_exp_f32_e32 v189, v189
	v_exp_f32_e32 v190, v190
	v_exp_f32_e32 v191, v191
	v_exp_f32_e32 v192, v192
	v_exp_f32_e32 v175, v175
	v_exp_f32_e32 v177, v177
	v_exp_f32_e32 v180, v180
	v_exp_f32_e32 v183, v183
	v_exp_f32_e32 v187, v187
	v_exp_f32_e32 v188, v188
	v_exp_f32_e32 v152, v152
	v_pk_add_f32 v[202:203], v[172:173], v[174:175]
	v_pk_add_f32 v[214:215], v[176:177], v[178:179]
	v_pk_add_f32 v[202:203], v[202:203], v[180:181]
	v_pk_add_f32 v[214:215], v[214:215], v[182:183]
	v_pk_add_f32 v[202:203], v[202:203], v[184:185]
	v_pk_add_f32 v[214:215], v[214:215], v[186:187]
	v_pk_add_f32 v[202:203], v[202:203], v[188:189]
	v_pk_add_f32 v[214:215], v[214:215], v[190:191]
	v_pk_add_f32 v[202:203], v[202:203], v[206:207]
	v_pk_add_f32 v[214:215], v[214:215], v[210:211]
	v_pk_add_f32 v[202:203], v[202:203], v[212:213]
	s_nop 0
	v_pk_add_f32 v[202:203], v[202:203], v[214:215]
	s_nop 0
	v_add_f32_e32 v154, v202, v203
	v_add_f32_e32 v154, v152, v154
	v_add_f32_e32 v154, v171, v154
	v_add_f32_e32 v154, v192, v154
	v_add_f32_e32 v154, v205, v154
	v_add_f32_e32 v154, v209, v154
	s_branch .LBB0_798

; DI void attn_tile(const LAS bf16_t* Ks, const LAS bf16_t* Vt, int vstride, const bf16x8 (&qf)[4], f32x16 (&O)[2], float& m, float& l,
;                   int t, int tw, int nt, int r, int h, int base, int stride, int dmax, bool ok, const LAS float* btl) {
;     ...
;   if (dmin >= 128 && dmaxw < dmax) {
;     const float cl = ok ? QK_SCALE2 : 0.f, bl = ok ? btl[128] : -1e30f;
;     float mr = -3e38f;
; #pragma unroll
;     for (int sub = 0; sub < 2; ++sub)
; #pragma unroll
;       for (int reg = 0; reg < 16; ++reg) mr = fmaxf(mr, s[sub][reg]);
;     float mx = mr * cl + bl; mx = fmaxf(mx, __shfl_xor(mx, 32));
;     mn = fmaxf(m, mx);
;     const float off = bl - mn;
; #pragma unroll
;     for (int sub = 0; sub < 2; ++sub)
; #pragma unroll
;       for (int reg = 0; reg < 16; ++reg) { const float e = __builtin_amdgcn_exp2f(s[sub][reg] * cl + off); s[sub][reg] = e; ls += e; }
.LBB0_805:
	s_mov_b32 s0, 0xff61b1e6
	v_max3_f32 v150, v50, s0, v51
	v_max3_f32 v150, v150, v52, v53
	v_max3_f32 v150, v150, v54, v55
	v_max3_f32 v150, v150, v56, v57
	v_max3_f32 v150, v150, v58, v59
	v_max3_f32 v150, v150, v60, v61
	v_max3_f32 v150, v150, v62, v63
	v_max3_f32 v150, v150, v64, v65
	v_max3_f32 v150, v150, v34, v35
	v_max3_f32 v150, v150, v36, v37
	v_max3_f32 v150, v150, v38, v39
	ds_read_b32 v33, v158 offset:512
	v_max3_f32 v150, v150, v40, v41
	v_max3_f32 v150, v150, v42, v43
	v_max3_f32 v150, v150, v44, v45
	v_max3_f32 v150, v150, v46, v47
	v_max3_f32 v150, v150, v48, v49
	s_waitcnt lgkmcnt(0)
	v_fmamk_f32 v150, v150, 0x3e38aa3b, v33
	v_mov_b32_e32 v151, v150
	s_nop 1
	v_permlane32_swap_b32_e32 v150, v151
	v_max3_f32 v151, v170, v150, v151
	v_sub_f32_e32 v153, v33, v151
	v_fmamk_f32 v33, v50, 0x3e38aa3b, v153
	v_fmamk_f32 v50, v51, 0x3e38aa3b, v153
	v_exp_f32_e32 v205, v33
	v_fmamk_f32 v51, v52, 0x3e38aa3b, v153
	v_exp_f32_e32 v206, v50
	v_fmamk_f32 v52, v53, 0x3e38aa3b, v153
	v_exp_f32_e32 v207, v51
	v_exp_f32_e32 v209, v52
	v_fmamk_f32 v50, v54, 0x3e38aa3b, v153
	v_add_f32_e32 v33, 0, v205
	v_exp_f32_e32 v210, v50
	v_fmamk_f32 v50, v55, 0x3e38aa3b, v153
	v_add_f32_e32 v33, v206, v33
	v_exp_f32_e32 v211, v50
	v_fmamk_f32 v50, v56, 0x3e38aa3b, v153
	v_add_f32_e32 v33, v207, v33
	v_exp_f32_e32 v212, v50
	v_fmamk_f32 v50, v57, 0x3e38aa3b, v153
	v_add_f32_e32 v33, v209, v33
	v_exp_f32_e32 v213, v50
	v_fmamk_f32 v50, v58, 0x3e38aa3b, v153
	v_add_f32_e32 v33, v210, v33
	v_exp_f32_e32 v171, v50
	v_fmamk_f32 v50, v59, 0x3e38aa3b, v153
	v_add_f32_e32 v33, v211, v33
	v_exp_f32_e32 v172, v50
	v_fmamk_f32 v50, v60, 0x3e38aa3b, v153
	v_add_f32_e32 v33, v212, v33
	v_exp_f32_e32 v173, v50
	v_fmamk_f32 v50, v61, 0x3e38aa3b, v153
	v_add_f32_e32 v33, v213, v33
	v_exp_f32_e32 v174, v50
	v_fmamk_f32 v50, v62, 0x3e38aa3b, v153
	v_add_f32_e32 v33, v171, v33
	v_exp_f32_e32 v176, v50
	v_fmamk_f32 v50, v63, 0x3e38aa3b, v153
	v_add_f32_e32 v33, v172, v33
	v_exp_f32_e32 v178, v50
	v_fmamk_f32 v50, v64, 0x3e38aa3b, v153
	v_add_f32_e32 v33, v173, v33
	v_exp_f32_e32 v181, v50
	v_fmamk_f32 v50, v65, 0x3e38aa3b, v153
	v_add_f32_e32 v33, v174, v33
	v_exp_f32_e32 v185, v50
	v_fmamk_f32 v34, v34, 0x3e38aa3b, v153
	v_add_f32_e32 v33, v176, v33
	v_exp_f32_e32 v179, v34
	v_fmamk_f32 v34, v35, 0x3e38aa3b, v153
	v_add_f32_e32 v33, v178, v33
	v_exp_f32_e32 v182, v34
	v_fmamk_f32 v34, v36, 0x3e38aa3b, v153
	v_add_f32_e32 v33, v181, v33
	v_exp_f32_e32 v184, v34
	v_fmamk_f32 v34, v37, 0x3e38aa3b, v153
	v_add_f32_e32 v33, v185, v33
	v_exp_f32_e32 v186, v34
	v_fmamk_f32 v34, v38, 0x3e38aa3b, v153
	v_add_f32_e32 v33, v179, v33
	v_exp_f32_e32 v189, v34
	v_fmamk_f32 v34, v39, 0x3e38aa3b, v153
	v_add_f32_e32 v33, v182, v33
	v_exp_f32_e32 v190, v34
	v_fmamk_f32 v34, v40, 0x3e38aa3b, v153
	v_add_f32_e32 v33, v184, v33
	v_exp_f32_e32 v191, v34
	v_fmamk_f32 v34, v41, 0x3e38aa3b, v153
	v_add_f32_e32 v33, v186, v33
	v_exp_f32_e32 v192, v34
	v_fmamk_f32 v34, v42, 0x3e38aa3b, v153
	v_add_f32_e32 v33, v189, v33
	v_exp_f32_e32 v175, v34
	v_fmamk_f32 v34, v43, 0x3e38aa3b, v153
	v_add_f32_e32 v33, v190, v33
	v_exp_f32_e32 v177, v34
	v_fmamk_f32 v34, v44, 0x3e38aa3b, v153
	v_add_f32_e32 v33, v191, v33
	v_exp_f32_e32 v180, v34
	v_fmamk_f32 v34, v45, 0x3e38aa3b, v153
	v_add_f32_e32 v33, v192, v33
	v_exp_f32_e32 v183, v34
	v_fmamk_f32 v34, v46, 0x3e38aa3b, v153
	v_add_f32_e32 v33, v175, v33
	v_exp_f32_e32 v187, v34
	v_fmamk_f32 v34, v47, 0x3e38aa3b, v153
	v_add_f32_e32 v33, v177, v33
	v_exp_f32_e32 v188, v34
	v_fmamk_f32 v34, v48, 0x3e38aa3b, v153
	v_add_f32_e32 v33, v180, v33
	v_exp_f32_e32 v152, v34
	v_add_f32_e32 v33, v183, v33
	v_add_f32_e32 v33, v187, v33
	v_add_f32_e32 v34, v188, v33
	v_mul_f32_e32 v35, 0x3e38aa3b, v49
	v_pk_add_f32 v[154:155], v[152:153], v[34:35]
	v_cmp_gt_f32_e32 vcc, v151, v170
	s_cbranch_vccnz .LBB0_799
